# v19 + P4 skips the SSD-output queue loop when this WG already saw the queue exhausted before the phase-3 barrier (no extra atomic round trip and WG barriers before barrier 4)
# speedup vs baseline: 1.0372x; 1.0022x over previous
; #define PSTAMP(i) do { if (PROBE_SEG >= 20 && blockIdx.x == PROBE_BLK && threadIdx.x == 0) ((volatile LAS unsigned long long*)(ctlw + 32))[8 + (i)] = __builtin_amdgcn_s_memrealtime(); } while (0)
; #define QUEUE_LOOP(qi, total, ...) for (;;) { __syncthreads(); if (threadIdx.x == 0) ctlw[16] = __hip_atomic_fetch_add(qbase + 64 * (qi), 1u, __ATOMIC_RELAXED, __HIP_MEMORY_SCOPE_AGENT); \
;         __syncthreads(); const int u = (int)ctlw[16]; if (u >= (total)) break; __VA_ARGS__ }
; __device__ __forceinline__ void phase4(const Params& p, LAS unsigned char* lds, volatile LAS unsigned* ctlw, int vcu, int G, int qset) {
;     ...
;     QUEUE_LOOP(5, NBATCH * 16 * 8, { const int v = NBATCH * 16 * 8 - 1 - u;
;         ssd_out_unit<false>(p.ws, p.out, p.in[I_ALOG], p.in[I_DSKIP], p.in[I_SSDNW], p.in[I_SSM], p.in[I_SCONV], p.in[I_CONVW], p.in[I_CONVB], lds, (v >> 3) & 3, v >> 5, v & 7); })
;     PSTAMP(1);
.LBB0_1074:
	s_cmp_eq_u32 s98, 4
	s_cbranch_scc0 .Lp4_do
	v_cmp_eq_u32_e64 s[0:1], 0, v0
	s_branch .Lp4_after
